# epifuse: P1 SwiGLU batch 0 interleaved with the last 32 MFMAs of the K-loop (regs v226-243)
# speedup vs baseline: 1.0007x; 1.0007x over previous
; #define PG8_STAGE(bufoff, gbase, voff) do { _Pragma("unroll") for (int _i = 0; _i < 2; ++_i) \
;         __builtin_amdgcn_global_load_lds((const unsigned*)((const char*)(gbase) + (voff)[_i]), (PG8_LAS unsigned*)(lds + (bufoff) + ldsw + _i * 8192), 16, 0, 0); } while (0)
; #define PG8_LDA(dst, b, h) do { _Pragma("unroll") for (int m = 0; m < 4; ++m) _Pragma("unroll") for (int k = 0; k < 2; ++k) dst[m][k] = *(const PG8_LAS bf16x8*)(lds + PG8_SA(b, h) + aoff + m * 2048 + k * 1024); } while (0)
; #define PG8_LDB(dst, b, h) do { _Pragma("unroll") for (int n = 0; n < 2; ++n) _Pragma("unroll") for (int k = 0; k < 2; ++k) dst[n][k] = *(const PG8_LAS bf16x8*)(lds + PG8_SB(b, h) + boff + n * 2048 + k * 1024); } while (0)
; #define PG8_MMA(ai, bj, At, Bt) do { __builtin_amdgcn_s_setprio(1); _Pragma("unroll") for (int m = 0; m < 4; ++m) _Pragma("unroll") for (int n = 0; n < 2; ++n) _Pragma("unroll") for (int k = 0; k < 2; ++k) \
;         acc[ai][bj][m][n] = __builtin_amdgcn_mfma_f32_16x16x32_bf16(Bt[n][k], At[m][k], acc[ai][bj][m][n], 0, 0, 0); __builtin_amdgcn_s_setprio(0); } while (0)
; #define PG8_WAIT_V(n) asm volatile("s_waitcnt vmcnt(" #n ")" ::: "memory")
; #define PG8_WAIT_L(n) asm volatile("s_waitcnt lgkmcnt(" #n ")" ::: "memory")
; #define PG8_BAR __builtin_amdgcn_s_barrier()
; #define PG8_SCHED __builtin_amdgcn_sched_barrier(0)
; template <class Epi, class Sched, bool ALIGN_EPI = false, bool SP2 = false>
; __device__ __forceinline__ void gemm_phase(PG8_LAS unsigned char* lds, const Gemm g, const Sched& S, const Epi& E) {
;     ...
;             PG8_WAIT_V(8); PG8_WAIT_L(0); PG8_BAR; PG8_MMA(1, 0, At, B0); PG8_MMA(1, 1, At, B1); PG8_BAR; PG8_SCHED;
;             PG8_LDB(B0, 1, 0); PG8_LDB(B1, 1, 1); PG8_SCHED; PG8_LDA(At, 1, 0); PG8_STAGE(PG8_SA(0, 1), a2 + hstep, voffA);
;             PG8_WAIT_V(8); PG8_WAIT_L(0); PG8_BAR; PG8_MMA(0, 0, At, B0); PG8_MMA(0, 1, At, B1); PG8_BAR; PG8_SCHED;
.Lrw0_b1:
	s_waitcnt lgkmcnt(0)
	s_barrier
	s_setprio 1
	s_waitcnt lgkmcnt(0)
	v_mfma_f32_16x16x32_bf16 v[60:63], v[144:147], v[182:185], v[60:63]
	v_mfma_f32_16x16x32_bf16 v[56:59], v[158:161], v[182:185], v[56:59]
	v_mfma_f32_16x16x32_bf16 v[44:47], v[144:147], v[190:193], v[44:47]
	v_mfma_f32_16x16x32_bf16 v[40:43], v[158:161], v[190:193], v[40:43]
	v_mfma_f32_16x16x32_bf16 v[28:31], v[144:147], v[202:205], v[28:31]
	v_mfma_f32_16x16x32_bf16 v[24:27], v[158:161], v[202:205], v[24:27]
	v_mfma_f32_16x16x32_bf16 v[12:15], v[144:147], v[210:213], v[12:15]
	v_mfma_f32_16x16x32_bf16 v[8:11], v[158:161], v[210:213], v[8:11]
	v_mfma_f32_16x16x32_bf16 v[60:63], v[154:157], v[186:189], v[60:63]
	v_mfma_f32_16x16x32_bf16 v[56:59], v[162:165], v[186:189], v[56:59]
	v_mfma_f32_16x16x32_bf16 v[44:47], v[154:157], v[198:201], v[44:47]
	v_mfma_f32_16x16x32_bf16 v[40:43], v[162:165], v[198:201], v[40:43]
	v_mfma_f32_16x16x32_bf16 v[28:31], v[154:157], v[206:209], v[28:31]
	v_mfma_f32_16x16x32_bf16 v[24:27], v[162:165], v[206:209], v[24:27]
	v_mfma_f32_16x16x32_bf16 v[12:15], v[154:157], v[214:217], v[12:15]
	v_mfma_f32_16x16x32_bf16 v[8:11], v[162:165], v[214:217], v[8:11]
	s_setprio 0
	s_setprio 1
	v_mfma_f32_16x16x32_bf16 v[52:55], v[166:169], v[182:185], v[52:55]
	v_mfma_f32_16x16x32_bf16 v[48:51], v[174:177], v[182:185], v[48:51]
	v_mfma_f32_16x16x32_bf16 v[36:39], v[166:169], v[190:193], v[36:39]
	v_mfma_f32_16x16x32_bf16 v[32:35], v[174:177], v[190:193], v[32:35]
	v_mfma_f32_16x16x32_bf16 v[20:23], v[166:169], v[202:205], v[20:23]
	v_mfma_f32_16x16x32_bf16 v[16:19], v[174:177], v[202:205], v[16:19]
	v_mfma_f32_16x16x32_bf16 v[4:7], v[166:169], v[210:213], v[4:7]
	v_mfma_f32_16x16x32_bf16 v[0:3], v[174:177], v[210:213], v[0:3]
	v_mfma_f32_16x16x32_bf16 v[52:55], v[170:173], v[186:189], v[52:55]
	v_mfma_f32_16x16x32_bf16 v[48:51], v[178:181], v[186:189], v[48:51]
	v_mfma_f32_16x16x32_bf16 v[36:39], v[170:173], v[198:201], v[36:39]
	v_mfma_f32_16x16x32_bf16 v[32:35], v[178:181], v[198:201], v[32:35]
	v_mfma_f32_16x16x32_bf16 v[20:23], v[170:173], v[206:209], v[20:23]
	v_mfma_f32_16x16x32_bf16 v[16:19], v[178:181], v[206:209], v[16:19]
	v_mfma_f32_16x16x32_bf16 v[4:7], v[170:173], v[214:217], v[4:7]
	v_mfma_f32_16x16x32_bf16 v[0:3], v[178:181], v[214:217], v[0:3]
	s_setprio 0
	s_barrier
	s_add_i32 s51, 0, 0x18000
	s_add_i32 s52, 0, 0x1c000
	v_add_u32_e32 v162, s51, v149
	v_add_u32_e32 v178, s52, v149
	ds_read_b128 v[144:147], v162
	ds_read_b128 v[154:157], v162 offset:1024
	ds_read_b128 v[158:161], v162 offset:2048
	ds_read_b128 v[162:165], v162 offset:3072
	ds_read_b128 v[166:169], v178
	ds_read_b128 v[170:173], v178 offset:1024
	ds_read_b128 v[174:177], v178 offset:2048
	ds_read_b128 v[178:181], v178 offset:3072
	s_add_u32 s28, s28, 0x40000
	s_addc_u32 s29, s29, 0
	s_mov_b32 m0, s35
	v_lshl_add_u64 v[224:225], s[28:29], 0, v[128:129]
	ds_read_b128 v[182:185], v153 offset:32768
	ds_read_b128 v[186:189], v153 offset:33792
	ds_read_b128 v[190:193], v153 offset:34816
	ds_read_b128 v[198:201], v153 offset:35840
	ds_read_b128 v[202:205], v153 offset:36864
	ds_read_b128 v[206:209], v153 offset:37888
	ds_read_b128 v[210:213], v153 offset:38912
	ds_read_b128 v[214:217], v153 offset:39936
	global_load_lds_dwordx4 v[224:225], off
	v_lshl_add_u64 v[224:225], s[28:29], 0, v[132:133]
	s_mov_b32 m0, s36
	s_nop 0
	global_load_lds_dwordx4 v[224:225], off
	s_waitcnt vmcnt(8)
	s_waitcnt lgkmcnt(0)
	s_barrier
	s_setprio 1
	s_waitcnt lgkmcnt(0)
	v_mfma_f32_16x16x32_bf16 v[124:127], v[144:147], v[182:185], v[124:127]
	v_mfma_f32_16x16x32_bf16 v[120:123], v[158:161], v[182:185], v[120:123]
	v_mfma_f32_16x16x32_bf16 v[108:111], v[144:147], v[190:193], v[108:111]
	v_mfma_f32_16x16x32_bf16 v[104:107], v[158:161], v[190:193], v[104:107]
	v_mfma_f32_16x16x32_bf16 v[92:95], v[144:147], v[202:205], v[92:95]
	v_mfma_f32_16x16x32_bf16 v[88:91], v[158:161], v[202:205], v[88:91]
	v_mfma_f32_16x16x32_bf16 v[76:79], v[144:147], v[210:213], v[76:79]
	v_mfma_f32_16x16x32_bf16 v[72:75], v[158:161], v[210:213], v[72:75]
	v_mfma_f32_16x16x32_bf16 v[124:127], v[154:157], v[186:189], v[124:127]
	v_mfma_f32_16x16x32_bf16 v[120:123], v[162:165], v[186:189], v[120:123]
	v_mfma_f32_16x16x32_bf16 v[108:111], v[154:157], v[198:201], v[108:111]
	v_mfma_f32_16x16x32_bf16 v[104:107], v[162:165], v[198:201], v[104:107]
	v_mfma_f32_16x16x32_bf16 v[92:95], v[154:157], v[206:209], v[92:95]
	v_mfma_f32_16x16x32_bf16 v[88:91], v[162:165], v[206:209], v[88:91]
	v_mfma_f32_16x16x32_bf16 v[76:79], v[154:157], v[214:217], v[76:79]
	v_mfma_f32_16x16x32_bf16 v[72:75], v[162:165], v[214:217], v[72:75]
	s_setprio 0
	s_setprio 1
	v_mfma_f32_16x16x32_bf16 v[116:119], v[166:169], v[182:185], v[116:119]
	v_mfma_f32_16x16x32_bf16 v[112:115], v[174:177], v[182:185], v[112:115]
	v_mfma_f32_16x16x32_bf16 v[100:103], v[166:169], v[190:193], v[100:103]
	v_mfma_f32_16x16x32_bf16 v[96:99], v[174:177], v[190:193], v[96:99]
	v_mfma_f32_16x16x32_bf16 v[84:87], v[166:169], v[202:205], v[84:87]
	v_mfma_f32_16x16x32_bf16 v[80:83], v[174:177], v[202:205], v[80:83]
	v_mfma_f32_16x16x32_bf16 v[68:71], v[166:169], v[210:213], v[68:71]
	v_mfma_f32_16x16x32_bf16 v[64:67], v[174:177], v[210:213], v[64:67]
	v_mfma_f32_16x16x32_bf16 v[116:119], v[170:173], v[186:189], v[116:119]
	v_mfma_f32_16x16x32_bf16 v[112:115], v[178:181], v[186:189], v[112:115]
	v_mfma_f32_16x16x32_bf16 v[100:103], v[170:173], v[198:201], v[100:103]
	v_mfma_f32_16x16x32_bf16 v[96:99], v[178:181], v[198:201], v[96:99]
	v_mfma_f32_16x16x32_bf16 v[84:87], v[170:173], v[206:209], v[84:87]
	v_mfma_f32_16x16x32_bf16 v[80:83], v[178:181], v[206:209], v[80:83]
	v_mfma_f32_16x16x32_bf16 v[68:71], v[170:173], v[214:217], v[68:71]
	v_mfma_f32_16x16x32_bf16 v[64:67], v[178:181], v[214:217], v[64:67]
	s_setprio 0
	s_barrier
; #define PG8_STAGE(bufoff, gbase, voff) do { _Pragma("unroll") for (int _i = 0; _i < 2; ++_i) \
;         __builtin_amdgcn_global_load_lds((const unsigned*)((const char*)(gbase) + (voff)[_i]), (PG8_LAS unsigned*)(lds + (bufoff) + ldsw + _i * 8192), 16, 0, 0); } while (0)
; #define PG8_LDA(dst, b, h) do { _Pragma("unroll") for (int m = 0; m < 4; ++m) _Pragma("unroll") for (int k = 0; k < 2; ++k) dst[m][k] = *(const PG8_LAS bf16x8*)(lds + PG8_SA(b, h) + aoff + m * 2048 + k * 1024); } while (0)
; #define PG8_MMA(ai, bj, At, Bt) do { __builtin_amdgcn_s_setprio(1); _Pragma("unroll") for (int m = 0; m < 4; ++m) _Pragma("unroll") for (int n = 0; n < 2; ++n) _Pragma("unroll") for (int k = 0; k < 2; ++k) \
;         acc[ai][bj][m][n] = __builtin_amdgcn_mfma_f32_16x16x32_bf16(Bt[n][k], At[m][k], acc[ai][bj][m][n], 0, 0, 0); __builtin_amdgcn_s_setprio(0); } while (0)
; #define PG8_WAIT_V(n) asm volatile("s_waitcnt vmcnt(" #n ")" ::: "memory")
; #define PG8_WAIT_L(n) asm volatile("s_waitcnt lgkmcnt(" #n ")" ::: "memory")
; #define PG8_BAR __builtin_amdgcn_s_barrier()
; #define PG8_SCHED __builtin_amdgcn_sched_barrier(0)
; template <class Epi, class Sched, bool ALIGN_EPI = false, bool SP2 = false>
; __device__ __forceinline__ void gemm_phase(PG8_LAS unsigned char* lds, const Gemm g, const Sched& S, const Epi& E) {
;     ...
;             PG8_LDA(At, 1, 1); PG8_STAGE(PG8_SB(1, 0), b3, voffB); PG8_STAGE(PG8_SB(1, 1), b3 + hstep, voffB); PG8_STAGE(PG8_SA(1, 0), a3, voffA);
;             PG8_WAIT_V(8); PG8_WAIT_L(0); PG8_BAR; PG8_MMA(1, 0, At, B0); PG8_MMA(1, 1, At, B1); PG8_BAR; PG8_SCHED;
	s_add_i32 s28, s51, s30
	v_lshl_add_u64 v[194:195], v[194:195], 0, s[10:11]
	s_mov_b32 m0, s28
	ds_read_b128 v[182:185], v153 offset:49152
	ds_read_b128 v[186:189], v153 offset:50176
	ds_read_b128 v[190:193], v153 offset:51200
	ds_read_b128 v[198:201], v153 offset:52224
	ds_read_b128 v[202:205], v153 offset:53248
	ds_read_b128 v[206:209], v153 offset:54272
	ds_read_b128 v[210:213], v153 offset:55296
	ds_read_b128 v[214:217], v153 offset:56320
	global_load_lds_dwordx4 v[194:195], off
	s_add_i32 m0, s28, 0x2000
	s_add_u32 s26, s26, 0x40080
	v_lshl_add_u64 v[194:195], v[218:219], 0, s[10:11]
	s_addc_u32 s27, s27, 0
	s_add_i32 s28, s52, s30
	global_load_lds_dwordx4 v[194:195], off
	v_lshl_add_u64 v[194:195], s[26:27], 0, v[130:131]
	s_mov_b32 m0, s28
	s_nop 0
	global_load_lds_dwordx4 v[194:195], off
	v_lshl_add_u64 v[194:195], s[26:27], 0, v[134:135]
	s_add_i32 m0, s28, 0x2000
	s_nop 0
	global_load_lds_dwordx4 v[194:195], off
	v_lshl_add_u64 v[194:195], v[220:221], 0, s[10:11]
	s_mov_b32 m0, s39
	s_nop 0
	global_load_lds_dwordx4 v[194:195], off
	v_lshl_add_u64 v[194:195], v[222:223], 0, s[10:11]
	s_mov_b32 m0, s40
	s_nop 0
	global_load_lds_dwordx4 v[194:195], off
	s_waitcnt vmcnt(8)
	s_waitcnt lgkmcnt(0)
	s_barrier
	s_setprio 1
	s_waitcnt lgkmcnt(0)
	s_cmp_eq_u32 s50, 12
	s_cbranch_scc1 .Lfz1_tail
	v_mfma_f32_16x16x32_bf16 v[60:63], v[144:147], v[182:185], v[60:63]
	v_mfma_f32_16x16x32_bf16 v[56:59], v[158:161], v[182:185], v[56:59]
	v_mfma_f32_16x16x32_bf16 v[44:47], v[144:147], v[190:193], v[44:47]
	v_mfma_f32_16x16x32_bf16 v[40:43], v[158:161], v[190:193], v[40:43]
	v_mfma_f32_16x16x32_bf16 v[28:31], v[144:147], v[202:205], v[28:31]
	v_mfma_f32_16x16x32_bf16 v[24:27], v[158:161], v[202:205], v[24:27]
	v_mfma_f32_16x16x32_bf16 v[12:15], v[144:147], v[210:213], v[12:15]
	v_mfma_f32_16x16x32_bf16 v[8:11], v[158:161], v[210:213], v[8:11]
	v_mfma_f32_16x16x32_bf16 v[60:63], v[154:157], v[186:189], v[60:63]
	v_mfma_f32_16x16x32_bf16 v[56:59], v[162:165], v[186:189], v[56:59]
	v_mfma_f32_16x16x32_bf16 v[44:47], v[154:157], v[198:201], v[44:47]
	v_mfma_f32_16x16x32_bf16 v[40:43], v[162:165], v[198:201], v[40:43]
	v_mfma_f32_16x16x32_bf16 v[28:31], v[154:157], v[206:209], v[28:31]
	v_mfma_f32_16x16x32_bf16 v[24:27], v[162:165], v[206:209], v[24:27]
	v_mfma_f32_16x16x32_bf16 v[12:15], v[154:157], v[214:217], v[12:15]
	v_mfma_f32_16x16x32_bf16 v[8:11], v[162:165], v[214:217], v[8:11]
	s_setprio 0
	s_setprio 1
	v_mfma_f32_16x16x32_bf16 v[52:55], v[166:169], v[182:185], v[52:55]
	v_mfma_f32_16x16x32_bf16 v[48:51], v[174:177], v[182:185], v[48:51]
	v_mfma_f32_16x16x32_bf16 v[36:39], v[166:169], v[190:193], v[36:39]
	v_mfma_f32_16x16x32_bf16 v[32:35], v[174:177], v[190:193], v[32:35]
	v_mfma_f32_16x16x32_bf16 v[20:23], v[166:169], v[202:205], v[20:23]
	v_mfma_f32_16x16x32_bf16 v[16:19], v[174:177], v[202:205], v[16:19]
	v_mfma_f32_16x16x32_bf16 v[4:7], v[166:169], v[210:213], v[4:7]
	v_mfma_f32_16x16x32_bf16 v[0:3], v[174:177], v[210:213], v[0:3]
	v_mfma_f32_16x16x32_bf16 v[52:55], v[170:173], v[186:189], v[52:55]
	v_mfma_f32_16x16x32_bf16 v[48:51], v[178:181], v[186:189], v[48:51]
	v_mfma_f32_16x16x32_bf16 v[36:39], v[170:173], v[198:201], v[36:39]
	v_mfma_f32_16x16x32_bf16 v[32:35], v[178:181], v[198:201], v[32:35]
	v_mfma_f32_16x16x32_bf16 v[20:23], v[170:173], v[206:209], v[20:23]
	v_mfma_f32_16x16x32_bf16 v[16:19], v[178:181], v[206:209], v[16:19]
	v_mfma_f32_16x16x32_bf16 v[4:7], v[170:173], v[214:217], v[4:7]
	v_mfma_f32_16x16x32_bf16 v[0:3], v[178:181], v[214:217], v[0:3]
	s_setprio 0
	s_barrier
	s_add_i32 s50, s50, 2
	s_add_u32 s24, s24, 0x100
	s_addc_u32 s25, s25, 0
	s_add_u32 s48, s48, 0x100
	s_addc_u32 s49, s49, 0
	s_cmp_gt_u32 s50, 13
	s_cbranch_scc0 .LBB0_293
	s_branch .Lrw0_x

; __device__ __forceinline__ unsigned cvt_pk_bf16(float lo, float hi) { unsigned r; asm volatile("v_cvt_pk_bf16_f32 %0, %1, %2" : "=v"(r) : "v"(lo), "v"(hi)); return r; }
; #define PG8_MMA(ai, bj, At, Bt) do { __builtin_amdgcn_s_setprio(1); _Pragma("unroll") for (int m = 0; m < 4; ++m) _Pragma("unroll") for (int n = 0; n < 2; ++n) _Pragma("unroll") for (int k = 0; k < 2; ++k) \
;         acc[ai][bj][m][n] = __builtin_amdgcn_mfma_f32_16x16x32_bf16(Bt[n][k], At[m][k], acc[ai][bj][m][n], 0, 0, 0); __builtin_amdgcn_s_setprio(0); } while (0)
; #define PG8_WAIT_V(n) asm volatile("s_waitcnt vmcnt(" #n ")" ::: "memory")
; #define PG8_WAIT_L(n) asm volatile("s_waitcnt lgkmcnt(" #n ")" ::: "memory")
; #define PG8_BAR __builtin_amdgcn_s_barrier()
; #define PG8_SCHED __builtin_amdgcn_sched_barrier(0)
;     __device__ __forceinline__ void operator()(const f32x4 (&acc)[2][2][4][2], const Unit& u, int wr, int wc, int fr, int fq) const {
;     ...
;                 for (int n = 0; n < 2; ++n)
; #pragma unroll
;                     for (int i = 0; i < 4; ++i) { const float g = acc[ai][0][m][n][i] * rsc, uu = acc[ai][1][m][n][i] * rsc; h[4 * n + i] = g * __builtin_amdgcn_rcpf(1.0f + __builtin_amdgcn_exp2f(g)) * uu; }
;                 u32x4 w; w.x = cvt_pk_bf16(h[0], h[1]); w.y = cvt_pk_bf16(h[2], h[3]); w.z = cvt_pk_bf16(h[4], h[5]); w.w = cvt_pk_bf16(h[6], h[7]);
; template <class Epi, class Sched, bool ALIGN_EPI = false, bool SP2 = false>
; __device__ __forceinline__ void gemm_phase(PG8_LAS unsigned char* lds, const Gemm g, const Sched& S, const Epi& E) {
;     ...
;             PG8_WAIT_V(8); PG8_WAIT_L(0); PG8_BAR; PG8_MMA(1, 0, At, B0); PG8_MMA(1, 1, At, B1); PG8_BAR; PG8_SCHED;
.Lfz1_tail:
	v_mov_b32_e32 v242, 1.0
	v_mfma_f32_16x16x32_bf16 v[60:63], v[144:147], v[182:185], v[60:63]
	v_exp_f32_e32 v226, v124
	v_exp_f32_e32 v227, v125
	v_mfma_f32_16x16x32_bf16 v[56:59], v[158:161], v[182:185], v[56:59]
	v_exp_f32_e32 v228, v126
	v_exp_f32_e32 v229, v127
	v_mfma_f32_16x16x32_bf16 v[44:47], v[144:147], v[190:193], v[44:47]
	v_exp_f32_e32 v230, v120
	v_exp_f32_e32 v231, v121
	v_mfma_f32_16x16x32_bf16 v[40:43], v[158:161], v[190:193], v[40:43]
	v_exp_f32_e32 v232, v122
	v_exp_f32_e32 v233, v123
	v_mfma_f32_16x16x32_bf16 v[28:31], v[144:147], v[202:205], v[28:31]
	v_exp_f32_e32 v234, v108
	v_exp_f32_e32 v235, v109
	v_mfma_f32_16x16x32_bf16 v[24:27], v[158:161], v[202:205], v[24:27]
	v_exp_f32_e32 v236, v110
	v_exp_f32_e32 v237, v111
	v_mfma_f32_16x16x32_bf16 v[12:15], v[144:147], v[210:213], v[12:15]
	v_exp_f32_e32 v238, v104
	v_exp_f32_e32 v239, v105
	v_mfma_f32_16x16x32_bf16 v[8:11], v[158:161], v[210:213], v[8:11]
	v_exp_f32_e32 v240, v106
	v_exp_f32_e32 v241, v107
	v_mfma_f32_16x16x32_bf16 v[60:63], v[154:157], v[186:189], v[60:63]
	v_pk_add_f32 v[226:227], v[226:227], v[242:243] op_sel_hi:[1,0]
	v_pk_add_f32 v[228:229], v[228:229], v[242:243] op_sel_hi:[1,0]
	v_mfma_f32_16x16x32_bf16 v[56:59], v[162:165], v[186:189], v[56:59]
	v_pk_add_f32 v[230:231], v[230:231], v[242:243] op_sel_hi:[1,0]
	v_pk_add_f32 v[232:233], v[232:233], v[242:243] op_sel_hi:[1,0]
	v_mfma_f32_16x16x32_bf16 v[44:47], v[154:157], v[198:201], v[44:47]
	v_pk_add_f32 v[234:235], v[234:235], v[242:243] op_sel_hi:[1,0]
	v_pk_add_f32 v[236:237], v[236:237], v[242:243] op_sel_hi:[1,0]
	v_mfma_f32_16x16x32_bf16 v[40:43], v[162:165], v[198:201], v[40:43]
	v_pk_add_f32 v[238:239], v[238:239], v[242:243] op_sel_hi:[1,0]
	v_pk_add_f32 v[240:241], v[240:241], v[242:243] op_sel_hi:[1,0]
	v_mfma_f32_16x16x32_bf16 v[28:31], v[154:157], v[206:209], v[28:31]
	v_rcp_f32_e32 v226, v226
	v_rcp_f32_e32 v227, v227
	v_mfma_f32_16x16x32_bf16 v[24:27], v[162:165], v[206:209], v[24:27]
	v_rcp_f32_e32 v228, v228
	v_rcp_f32_e32 v229, v229
	v_mfma_f32_16x16x32_bf16 v[12:15], v[154:157], v[214:217], v[12:15]
	v_rcp_f32_e32 v230, v230
	v_rcp_f32_e32 v231, v231
	v_mfma_f32_16x16x32_bf16 v[8:11], v[162:165], v[214:217], v[8:11]
	v_rcp_f32_e32 v232, v232
	v_rcp_f32_e32 v233, v233
	s_setprio 0
	s_setprio 1
	v_mfma_f32_16x16x32_bf16 v[52:55], v[166:169], v[182:185], v[52:55]
	v_rcp_f32_e32 v234, v234
	v_rcp_f32_e32 v235, v235
	v_mfma_f32_16x16x32_bf16 v[48:51], v[174:177], v[182:185], v[48:51]
	v_rcp_f32_e32 v236, v236
	v_rcp_f32_e32 v237, v237
	v_mfma_f32_16x16x32_bf16 v[36:39], v[166:169], v[190:193], v[36:39]
	v_rcp_f32_e32 v238, v238
	v_rcp_f32_e32 v239, v239
	v_mfma_f32_16x16x32_bf16 v[32:35], v[174:177], v[190:193], v[32:35]
	v_rcp_f32_e32 v240, v240
	v_rcp_f32_e32 v241, v241
	v_mfma_f32_16x16x32_bf16 v[20:23], v[166:169], v[202:205], v[20:23]
	v_pk_mul_f32 v[124:125], v[124:125], v[226:227]
	v_pk_mul_f32 v[126:127], v[126:127], v[228:229]
	v_mfma_f32_16x16x32_bf16 v[16:19], v[174:177], v[202:205], v[16:19]
	v_pk_mul_f32 v[120:121], v[120:121], v[230:231]
	v_pk_mul_f32 v[122:123], v[122:123], v[232:233]
	v_mfma_f32_16x16x32_bf16 v[4:7], v[166:169], v[210:213], v[4:7]
	v_pk_mul_f32 v[108:109], v[108:109], v[234:235]
	v_pk_mul_f32 v[110:111], v[110:111], v[236:237]
	v_mfma_f32_16x16x32_bf16 v[0:3], v[174:177], v[210:213], v[0:3]
	v_pk_mul_f32 v[104:105], v[104:105], v[238:239]
	v_pk_mul_f32 v[106:107], v[106:107], v[240:241]
	v_mfma_f32_16x16x32_bf16 v[52:55], v[170:173], v[186:189], v[52:55]
	v_pk_mul_f32 v[116:117], v[124:125], v[116:117]
	v_pk_mul_f32 v[118:119], v[126:127], v[118:119]
	v_mfma_f32_16x16x32_bf16 v[48:51], v[178:181], v[186:189], v[48:51]
	v_pk_mul_f32 v[112:113], v[120:121], v[112:113]
	v_pk_mul_f32 v[114:115], v[122:123], v[114:115]
	v_mfma_f32_16x16x32_bf16 v[36:39], v[170:173], v[198:201], v[36:39]
	v_pk_mul_f32 v[100:101], v[108:109], v[100:101]
	v_pk_mul_f32 v[102:103], v[110:111], v[102:103]
	v_mfma_f32_16x16x32_bf16 v[32:35], v[178:181], v[198:201], v[32:35]
	v_pk_mul_f32 v[96:97], v[104:105], v[96:97]
	v_pk_mul_f32 v[98:99], v[106:107], v[98:99]
	v_mfma_f32_16x16x32_bf16 v[20:23], v[170:173], v[206:209], v[20:23]
	v_cvt_pk_bf16_f32 v120, v116, v117
	v_cvt_pk_bf16_f32 v121, v118, v119
	v_mfma_f32_16x16x32_bf16 v[16:19], v[178:181], v[206:209], v[16:19]
	v_cvt_pk_bf16_f32 v122, v112, v113
	v_cvt_pk_bf16_f32 v123, v114, v115
	v_mfma_f32_16x16x32_bf16 v[4:7], v[170:173], v[214:217], v[4:7]
	v_cvt_pk_bf16_f32 v104, v100, v101
	v_cvt_pk_bf16_f32 v105, v102, v103
	v_mfma_f32_16x16x32_bf16 v[0:3], v[178:181], v[214:217], v[0:3]
	v_cvt_pk_bf16_f32 v106, v96, v97
	v_cvt_pk_bf16_f32 v107, v98, v99
	s_setprio 0
	s_barrier
	s_add_i32 s50, s50, 2
	s_add_u32 s24, s24, 0x100
	s_addc_u32 s25, s25, 0
	s_add_u32 s48, s48, 0x100
	s_addc_u32 s49, s49, 0
	s_branch .Lrw0_x

; __device__ __forceinline__ unsigned cvt_pk_bf16(float lo, float hi) { unsigned r; asm volatile("v_cvt_pk_bf16_f32 %0, %1, %2" : "=v"(r) : "v"(lo), "v"(hi)); return r; }
;     __device__ __forceinline__ void operator()(const f32x4 (&acc)[2][2][4][2], const Unit& u, int wr, int wc, int fr, int fq) const {
;         const int row0 = u.pm * BM + wr * 64 + fr, col0 = u.pn * 128 + wc * 32 + 8 * fq;
; #pragma unroll
;         for (int ai = 0; ai < 2; ++ai)
; #pragma unroll
;             for (int m = 0; m < 4; ++m) {
;                 bf16_t* p = O + (size_t)(row0 + ai * HALF + m * 16) * ldc + col0;
;                 float h[8]; const float rsc = rs ? rs[row0 + ai * HALF + m * 16] : 1.0f;
; #pragma unroll
;                 for (int n = 0; n < 2; ++n)
; #pragma unroll
;                     for (int i = 0; i < 4; ++i) { const float g = acc[ai][0][m][n][i] * rsc, uu = acc[ai][1][m][n][i] * rsc; h[4 * n + i] = g * __builtin_amdgcn_rcpf(1.0f + __builtin_amdgcn_exp2f(g)) * uu; }
;                 u32x4 w; w.x = cvt_pk_bf16(h[0], h[1]); w.y = cvt_pk_bf16(h[2], h[3]); w.z = cvt_pk_bf16(h[4], h[5]); w.w = cvt_pk_bf16(h[6], h[7]);
;                 *(u32x4*)p = w;
.LBB0_296:
	s_mov_b32 s98, 0x16000
	s_mov_b32 s99, 0
	s_mov_b32 s100, 0x6e000
	s_mov_b32 s101, 0
	v_readlane_b32 s24, v253, 47
	v_lshl_or_b32 v146, s45, 7, v150
	v_readlane_b32 s25, v253, 48
	v_lshl_add_u32 v154, s22, 8, v148
	v_ashrrev_i32_e32 v147, 31, v146
	s_nop 0
	v_mov_b64_e32 v[144:145], s[24:25]
	v_mad_i64_i32 v[198:199], s[24:25], v154, s44, v[144:145]
	v_lshlrev_b64 v[146:147], 1, v[146:147]
	v_lshl_add_u64 v[198:199], v[198:199], 0, v[146:147]
	v_lshl_add_u64 v[200:201], v[198:199], 0, s[98:99]
	v_lshl_add_u64 v[202:203], v[200:201], 0, s[98:99]
	v_lshl_add_u64 v[204:205], v[202:203], 0, s[98:99]
	v_lshl_add_u64 v[206:207], v[204:205], 0, s[100:101]
	v_lshl_add_u64 v[208:209], v[206:207], 0, s[98:99]
	v_lshl_add_u64 v[210:211], v[208:209], 0, s[98:99]
	v_lshl_add_u64 v[212:213], v[210:211], 0, s[98:99]
	v_exp_f32_e32 v226, v92
	v_exp_f32_e32 v227, v93
	v_exp_f32_e32 v228, v94
	v_exp_f32_e32 v229, v95
	v_exp_f32_e32 v230, v88
	v_exp_f32_e32 v231, v89
	v_exp_f32_e32 v232, v90
	v_exp_f32_e32 v233, v91
	v_exp_f32_e32 v234, v76
	v_exp_f32_e32 v235, v77
	v_exp_f32_e32 v236, v78
	v_exp_f32_e32 v237, v79
	v_exp_f32_e32 v238, v72
	v_exp_f32_e32 v239, v73
	v_exp_f32_e32 v240, v74
	v_exp_f32_e32 v241, v75
	v_pk_add_f32 v[226:227], v[226:227], v[242:243] op_sel_hi:[1,0]
	v_pk_add_f32 v[228:229], v[228:229], v[242:243] op_sel_hi:[1,0]
	v_pk_add_f32 v[230:231], v[230:231], v[242:243] op_sel_hi:[1,0]
	v_pk_add_f32 v[232:233], v[232:233], v[242:243] op_sel_hi:[1,0]
	v_pk_add_f32 v[234:235], v[234:235], v[242:243] op_sel_hi:[1,0]
	v_pk_add_f32 v[236:237], v[236:237], v[242:243] op_sel_hi:[1,0]
	v_pk_add_f32 v[238:239], v[238:239], v[242:243] op_sel_hi:[1,0]
	v_pk_add_f32 v[240:241], v[240:241], v[242:243] op_sel_hi:[1,0]
	v_rcp_f32_e32 v226, v226
	global_store_dwordx4 v[198:199], v[120:123], off
	v_rcp_f32_e32 v227, v227
	global_store_dwordx4 v[200:201], v[104:107], off
	v_rcp_f32_e32 v228, v228
	v_rcp_f32_e32 v229, v229
	v_rcp_f32_e32 v230, v230
	v_rcp_f32_e32 v231, v231
	v_rcp_f32_e32 v232, v232
	v_rcp_f32_e32 v233, v233
	v_rcp_f32_e32 v234, v234
	v_rcp_f32_e32 v235, v235
	v_rcp_f32_e32 v236, v236
	v_rcp_f32_e32 v237, v237
	v_rcp_f32_e32 v238, v238
	v_rcp_f32_e32 v239, v239
	v_rcp_f32_e32 v240, v240
	v_rcp_f32_e32 v241, v241
	v_pk_mul_f32 v[92:93], v[92:93], v[226:227]
	v_exp_f32_e32 v226, v60
	v_pk_mul_f32 v[94:95], v[94:95], v[228:229]
	v_exp_f32_e32 v227, v61
	v_pk_mul_f32 v[88:89], v[88:89], v[230:231]
	v_exp_f32_e32 v228, v62
	v_pk_mul_f32 v[90:91], v[90:91], v[232:233]
	v_exp_f32_e32 v229, v63
	v_pk_mul_f32 v[76:77], v[76:77], v[234:235]
	v_exp_f32_e32 v230, v56
	v_pk_mul_f32 v[78:79], v[78:79], v[236:237]
	v_exp_f32_e32 v231, v57
	v_pk_mul_f32 v[72:73], v[72:73], v[238:239]
	v_exp_f32_e32 v232, v58
	v_pk_mul_f32 v[74:75], v[74:75], v[240:241]
	v_exp_f32_e32 v233, v59
	v_pk_mul_f32 v[84:85], v[92:93], v[84:85]
	v_exp_f32_e32 v234, v44
	v_pk_mul_f32 v[86:87], v[94:95], v[86:87]
	v_exp_f32_e32 v235, v45
	v_pk_mul_f32 v[80:81], v[88:89], v[80:81]
	v_exp_f32_e32 v236, v46
	v_pk_mul_f32 v[82:83], v[90:91], v[82:83]
	v_exp_f32_e32 v237, v47
	v_pk_mul_f32 v[68:69], v[76:77], v[68:69]
	v_exp_f32_e32 v238, v40
	v_pk_mul_f32 v[70:71], v[78:79], v[70:71]
	v_exp_f32_e32 v239, v41
	v_pk_mul_f32 v[64:65], v[72:73], v[64:65]
	v_exp_f32_e32 v240, v42
	v_pk_mul_f32 v[66:67], v[74:75], v[66:67]
	v_exp_f32_e32 v241, v43
	v_pk_add_f32 v[226:227], v[226:227], v[242:243] op_sel_hi:[1,0]
	v_pk_add_f32 v[228:229], v[228:229], v[242:243] op_sel_hi:[1,0]
	v_pk_add_f32 v[230:231], v[230:231], v[242:243] op_sel_hi:[1,0]
	v_pk_add_f32 v[232:233], v[232:233], v[242:243] op_sel_hi:[1,0]
	v_pk_add_f32 v[234:235], v[234:235], v[242:243] op_sel_hi:[1,0]
	v_pk_add_f32 v[236:237], v[236:237], v[242:243] op_sel_hi:[1,0]
	v_pk_add_f32 v[238:239], v[238:239], v[242:243] op_sel_hi:[1,0]
	v_pk_add_f32 v[240:241], v[240:241], v[242:243] op_sel_hi:[1,0]
	v_rcp_f32_e32 v226, v226
	v_cvt_pk_bf16_f32 v88, v84, v85
	v_rcp_f32_e32 v227, v227
	v_cvt_pk_bf16_f32 v89, v86, v87
	v_rcp_f32_e32 v228, v228
	v_cvt_pk_bf16_f32 v90, v80, v81
	v_rcp_f32_e32 v229, v229
	v_cvt_pk_bf16_f32 v91, v82, v83
; __device__ __forceinline__ unsigned cvt_pk_bf16(float lo, float hi) { unsigned r; asm volatile("v_cvt_pk_bf16_f32 %0, %1, %2" : "=v"(r) : "v"(lo), "v"(hi)); return r; }
;     __device__ __forceinline__ void operator()(const f32x4 (&acc)[2][2][4][2], const Unit& u, int wr, int wc, int fr, int fq) const {
;         const int row0 = u.pm * BM + wr * 64 + fr, col0 = u.pn * 128 + wc * 32 + 8 * fq;
; #pragma unroll
;         for (int ai = 0; ai < 2; ++ai)
; #pragma unroll
;             for (int m = 0; m < 4; ++m) {
;                 bf16_t* p = O + (size_t)(row0 + ai * HALF + m * 16) * ldc + col0;
;                 float h[8]; const float rsc = rs ? rs[row0 + ai * HALF + m * 16] : 1.0f;
; #pragma unroll
;                 for (int n = 0; n < 2; ++n)
; #pragma unroll
;                     for (int i = 0; i < 4; ++i) { const float g = acc[ai][0][m][n][i] * rsc, uu = acc[ai][1][m][n][i] * rsc; h[4 * n + i] = g * __builtin_amdgcn_rcpf(1.0f + __builtin_amdgcn_exp2f(g)) * uu; }
;                 u32x4 w; w.x = cvt_pk_bf16(h[0], h[1]); w.y = cvt_pk_bf16(h[2], h[3]); w.z = cvt_pk_bf16(h[4], h[5]); w.w = cvt_pk_bf16(h[6], h[7]);
;                 *(u32x4*)p = w;
	v_rcp_f32_e32 v230, v230
	v_cvt_pk_bf16_f32 v72, v68, v69
	v_rcp_f32_e32 v231, v231
	v_cvt_pk_bf16_f32 v73, v70, v71
	v_rcp_f32_e32 v232, v232
	v_cvt_pk_bf16_f32 v74, v64, v65
	v_rcp_f32_e32 v233, v233
	v_cvt_pk_bf16_f32 v75, v66, v67
	v_rcp_f32_e32 v234, v234
	global_store_dwordx4 v[202:203], v[88:91], off
	v_rcp_f32_e32 v235, v235
	global_store_dwordx4 v[204:205], v[72:75], off
	v_rcp_f32_e32 v236, v236
	v_rcp_f32_e32 v237, v237
	v_rcp_f32_e32 v238, v238
	v_rcp_f32_e32 v239, v239
	v_rcp_f32_e32 v240, v240
	v_rcp_f32_e32 v241, v241
	v_pk_mul_f32 v[60:61], v[60:61], v[226:227]
	v_exp_f32_e32 v226, v28
	v_pk_mul_f32 v[62:63], v[62:63], v[228:229]
	v_exp_f32_e32 v227, v29
	v_pk_mul_f32 v[56:57], v[56:57], v[230:231]
	v_exp_f32_e32 v228, v30
	v_pk_mul_f32 v[58:59], v[58:59], v[232:233]
	v_exp_f32_e32 v229, v31
	v_pk_mul_f32 v[44:45], v[44:45], v[234:235]
	v_exp_f32_e32 v230, v24
	v_pk_mul_f32 v[46:47], v[46:47], v[236:237]
	v_exp_f32_e32 v231, v25
	v_pk_mul_f32 v[40:41], v[40:41], v[238:239]
	v_exp_f32_e32 v232, v26
	v_pk_mul_f32 v[42:43], v[42:43], v[240:241]
	v_exp_f32_e32 v233, v27
	v_pk_mul_f32 v[52:53], v[60:61], v[52:53]
	v_exp_f32_e32 v234, v12
	v_pk_mul_f32 v[54:55], v[62:63], v[54:55]
	v_exp_f32_e32 v235, v13
	v_pk_mul_f32 v[48:49], v[56:57], v[48:49]
	v_exp_f32_e32 v236, v14
	v_pk_mul_f32 v[50:51], v[58:59], v[50:51]
	v_exp_f32_e32 v237, v15
	v_pk_mul_f32 v[36:37], v[44:45], v[36:37]
	v_exp_f32_e32 v238, v8
	v_pk_mul_f32 v[38:39], v[46:47], v[38:39]
	v_exp_f32_e32 v239, v9
	v_pk_mul_f32 v[32:33], v[40:41], v[32:33]
	v_exp_f32_e32 v240, v10
	v_pk_mul_f32 v[34:35], v[42:43], v[34:35]
	v_exp_f32_e32 v241, v11
	v_pk_add_f32 v[226:227], v[226:227], v[242:243] op_sel_hi:[1,0]
	v_pk_add_f32 v[228:229], v[228:229], v[242:243] op_sel_hi:[1,0]
	v_pk_add_f32 v[230:231], v[230:231], v[242:243] op_sel_hi:[1,0]
	v_pk_add_f32 v[232:233], v[232:233], v[242:243] op_sel_hi:[1,0]
	v_pk_add_f32 v[234:235], v[234:235], v[242:243] op_sel_hi:[1,0]
	v_pk_add_f32 v[236:237], v[236:237], v[242:243] op_sel_hi:[1,0]
	v_pk_add_f32 v[238:239], v[238:239], v[242:243] op_sel_hi:[1,0]
	v_pk_add_f32 v[240:241], v[240:241], v[242:243] op_sel_hi:[1,0]
	v_rcp_f32_e32 v226, v226
	v_cvt_pk_bf16_f32 v56, v52, v53
	v_rcp_f32_e32 v227, v227
	v_cvt_pk_bf16_f32 v57, v54, v55
	v_rcp_f32_e32 v228, v228
	v_cvt_pk_bf16_f32 v58, v48, v49
	v_rcp_f32_e32 v229, v229
	v_cvt_pk_bf16_f32 v59, v50, v51
	v_rcp_f32_e32 v230, v230
	v_cvt_pk_bf16_f32 v40, v36, v37
	v_rcp_f32_e32 v231, v231
	v_cvt_pk_bf16_f32 v41, v38, v39
	v_rcp_f32_e32 v232, v232
	v_cvt_pk_bf16_f32 v42, v32, v33
	v_rcp_f32_e32 v233, v233
	v_cvt_pk_bf16_f32 v43, v34, v35
	v_rcp_f32_e32 v234, v234
	global_store_dwordx4 v[206:207], v[56:59], off
	v_rcp_f32_e32 v235, v235
	global_store_dwordx4 v[208:209], v[40:43], off
	v_rcp_f32_e32 v236, v236
	v_rcp_f32_e32 v237, v237
	v_rcp_f32_e32 v238, v238
	v_rcp_f32_e32 v239, v239
	v_rcp_f32_e32 v240, v240
	v_rcp_f32_e32 v241, v241
	v_pk_mul_f32 v[28:29], v[28:29], v[226:227]
	v_pk_mul_f32 v[30:31], v[30:31], v[228:229]
	v_pk_mul_f32 v[24:25], v[24:25], v[230:231]
	v_pk_mul_f32 v[26:27], v[26:27], v[232:233]
	v_pk_mul_f32 v[12:13], v[12:13], v[234:235]
	v_pk_mul_f32 v[14:15], v[14:15], v[236:237]
	v_pk_mul_f32 v[8:9], v[8:9], v[238:239]
	v_pk_mul_f32 v[10:11], v[10:11], v[240:241]
	v_pk_mul_f32 v[20:21], v[28:29], v[20:21]
	v_pk_mul_f32 v[22:23], v[30:31], v[22:23]
	v_pk_mul_f32 v[16:17], v[24:25], v[16:17]
	v_pk_mul_f32 v[18:19], v[26:27], v[18:19]
	v_pk_mul_f32 v[4:5], v[12:13], v[4:5]
	v_pk_mul_f32 v[6:7], v[14:15], v[6:7]
	v_pk_mul_f32 v[0:1], v[8:9], v[0:1]
	v_pk_mul_f32 v[2:3], v[10:11], v[2:3]
	v_cvt_pk_bf16_f32 v24, v20, v21
	v_cvt_pk_bf16_f32 v25, v22, v23
	v_cvt_pk_bf16_f32 v26, v16, v17
	v_cvt_pk_bf16_f32 v27, v18, v19
	v_cvt_pk_bf16_f32 v8, v4, v5
	v_cvt_pk_bf16_f32 v9, v6, v7
	v_cvt_pk_bf16_f32 v10, v0, v1
	v_cvt_pk_bf16_f32 v11, v2, v3
	global_store_dwordx4 v[210:211], v[24:27], off
	global_store_dwordx4 v[212:213], v[8:11], off
	s_andn2_b64 vcc, exec, s[0:1]
	s_mov_b64 s[0:1], -1
	s_cbranch_vccnz .LBB0_289
	s_andn2_b64 vcc, exec, s[4:5]
	s_cbranch_vccnz .LBB0_288
	s_barrier
	s_branch .LBB0_288
